# P8 sample-row mini GEMM: all 44 operand fragments of a wave requested up front (was a 3-deep rotating window), on top of the barrier edits
# speedup vs baseline: 1.0059x; 1.0000x over previous
; __device__ __forceinline__ unsigned f2bf(float f) { unsigned u = __float_as_uint(f); return (u + 0x7fffu + ((u >> 16) & 1u)) >> 16; }
; template <int MODE>
; __device__ __forceinline__ void mini_gemm(LAS unsigned char* lds, const bf16_t* A, const bf16_t* Bt, int K, int N, bf16_t* O, int ldc, const float* rstd, float* sumsq, int bx, int G, int tid, int wave, int lane) {
;     ...
;     for (int tile = bx; tile < ntiles; tile += G) {
;         const int m0 = (tile / ntn) * 32, n0 = (tile % ntn) * 32;
;         const bf16_t* ap = A + (size_t)(m0 + r) * K + wave * kw + 8 * hf; const bf16_t* bp = Bt + (size_t)(n0 + r) * K + wave * kw + 8 * hf;
;         f32x16 acc; for (int i = 0; i < 16; ++i) acc[i] = 0.f;
;         for (int k = 0; k < kw; k += 16) { const bf16x8 af = *(const bf16x8*)(ap + k), bf = *(const bf16x8*)(bp + k); acc = __builtin_amdgcn_mfma_f32_32x32x16_bf16(af, bf, acc, 0, 0, 0); }
;         __syncthreads();
; #pragma unroll
;         for (int i = 0; i < 16; ++i) red[(wave * 16 + i) * 64 + lane] = acc[i];
;         __syncthreads();
; #pragma unroll
;         for (int h2 = 0; h2 < 2; ++h2) {
;             const int e = tid + h2 * 512, i = e >> 6, ln = e & 63;
;             float v = 0.f;
; #pragma unroll
;             for (int w = 0; w < 8; ++w) v += red[(w * 16 + i) * 64 + ln];
;             const int row = m0 + (i & 3) + 8 * (i >> 2) + 4 * (ln >> 5), col = n0 + (ln & 31);
;             if (MODE == 0) { O[(size_t)row * ldc + col] = (bf16_t)f2bf(v * rstd[row]); }
;             else { O[(size_t)row * ldc + col] = (bf16_t)f2bf(v); float ss = v * v;
; #pragma unroll
;                 for (int o = 1; o < 32; o <<= 1) ss += __shfl_xor(ss, o);
;                 if ((ln & 31) == 0) atomicAdd(sumsq + row, ss); }
.LBB0_1296:
	s_ashr_i32 s0, s96, 31
	s_lshr_b32 s0, s0, 27
	s_add_i32 s0, s96, s0
	s_and_b32 s13, s0, 0xffffffe0
	v_or_b32_e32 v0, s13, v20
	s_ashr_i32 s12, s0, 5
	v_mad_i64_i32 v[54:55], s[0:1], v0, s10, v[16:17]
	s_mul_i32 s14, s12, 0xffd40000
	v_add_u32_e32 v4, s14, v32
	s_waitcnt lgkmcnt(0)
	v_ashrrev_i32_e32 v5, 31, v4
	v_lshl_add_u64 v[56:57], v[4:5], 1, v[18:19]
	s_lshl_b32 s0, s12, 10
	global_load_dwordx4 v[60:63], v[54:55], off
	global_load_dwordx4 v[148:151], v[56:57], off
	global_load_dwordx4 v[64:67], v[54:55], off offset:32
	global_load_dwordx4 v[152:155], v[56:57], off offset:32
	global_load_dwordx4 v[68:71], v[54:55], off offset:64
	global_load_dwordx4 v[156:159], v[56:57], off offset:64
	global_load_dwordx4 v[72:75], v[54:55], off offset:96
	global_load_dwordx4 v[160:163], v[56:57], off offset:96
	global_load_dwordx4 v[76:79], v[54:55], off offset:128
	global_load_dwordx4 v[164:167], v[56:57], off offset:128
	global_load_dwordx4 v[80:83], v[54:55], off offset:160
	global_load_dwordx4 v[168:171], v[56:57], off offset:160
	global_load_dwordx4 v[84:87], v[54:55], off offset:192
	global_load_dwordx4 v[180:183], v[56:57], off offset:192
	global_load_dwordx4 v[88:91], v[54:55], off offset:224
	global_load_dwordx4 v[184:187], v[56:57], off offset:224
	global_load_dwordx4 v[92:95], v[54:55], off offset:256
	global_load_dwordx4 v[188:191], v[56:57], off offset:256
	global_load_dwordx4 v[96:99], v[54:55], off offset:288
	global_load_dwordx4 v[192:195], v[56:57], off offset:288
	global_load_dwordx4 v[100:103], v[54:55], off offset:320
	global_load_dwordx4 v[196:199], v[56:57], off offset:320
	global_load_dwordx4 v[104:107], v[54:55], off offset:352
	global_load_dwordx4 v[200:203], v[56:57], off offset:352
	global_load_dwordx4 v[108:111], v[54:55], off offset:384
	global_load_dwordx4 v[204:207], v[56:57], off offset:384
	global_load_dwordx4 v[112:115], v[54:55], off offset:416
	global_load_dwordx4 v[208:211], v[56:57], off offset:416
	global_load_dwordx4 v[116:119], v[54:55], off offset:448
	global_load_dwordx4 v[212:215], v[56:57], off offset:448
	global_load_dwordx4 v[120:123], v[54:55], off offset:480
	global_load_dwordx4 v[216:219], v[56:57], off offset:480
	global_load_dwordx4 v[124:127], v[54:55], off offset:512
	global_load_dwordx4 v[220:223], v[56:57], off offset:512
	global_load_dwordx4 v[128:131], v[54:55], off offset:544
	global_load_dwordx4 v[224:227], v[56:57], off offset:544
	global_load_dwordx4 v[132:135], v[54:55], off offset:576
	global_load_dwordx4 v[228:231], v[56:57], off offset:576
	global_load_dwordx4 v[136:139], v[54:55], off offset:608
	global_load_dwordx4 v[232:235], v[56:57], off offset:608
	global_load_dwordx4 v[140:143], v[54:55], off offset:640
	global_load_dwordx4 v[236:239], v[56:57], off offset:640
	global_load_dwordx4 v[144:147], v[54:55], off offset:672
	global_load_dwordx4 v[240:243], v[56:57], off offset:672
	s_waitcnt vmcnt(42)
	v_mfma_f32_32x32x16_bf16 v[0:15], v[60:63], v[148:151], 0
	s_waitcnt vmcnt(40)
	v_mfma_f32_32x32x16_bf16 v[0:15], v[64:67], v[152:155], v[0:15]
	s_waitcnt vmcnt(38)
	v_mfma_f32_32x32x16_bf16 v[0:15], v[68:71], v[156:159], v[0:15]
	s_waitcnt vmcnt(36)
	v_mfma_f32_32x32x16_bf16 v[0:15], v[72:75], v[160:163], v[0:15]
	s_waitcnt vmcnt(34)
	v_mfma_f32_32x32x16_bf16 v[0:15], v[76:79], v[164:167], v[0:15]
	s_waitcnt vmcnt(32)
	v_mfma_f32_32x32x16_bf16 v[0:15], v[80:83], v[168:171], v[0:15]
	s_waitcnt vmcnt(30)
	v_mfma_f32_32x32x16_bf16 v[0:15], v[84:87], v[180:183], v[0:15]
	s_waitcnt vmcnt(28)
	v_mfma_f32_32x32x16_bf16 v[0:15], v[88:91], v[184:187], v[0:15]
	s_waitcnt vmcnt(26)
	v_mfma_f32_32x32x16_bf16 v[0:15], v[92:95], v[188:191], v[0:15]
	s_waitcnt vmcnt(24)
	v_mfma_f32_32x32x16_bf16 v[0:15], v[96:99], v[192:195], v[0:15]
	s_waitcnt vmcnt(22)
	v_mfma_f32_32x32x16_bf16 v[0:15], v[100:103], v[196:199], v[0:15]
	s_waitcnt vmcnt(20)
	v_mfma_f32_32x32x16_bf16 v[0:15], v[104:107], v[200:203], v[0:15]
	s_waitcnt vmcnt(18)
	v_mfma_f32_32x32x16_bf16 v[0:15], v[108:111], v[204:207], v[0:15]
	s_waitcnt vmcnt(16)
	v_mfma_f32_32x32x16_bf16 v[0:15], v[112:115], v[208:211], v[0:15]
	s_waitcnt vmcnt(14)
	v_mfma_f32_32x32x16_bf16 v[0:15], v[116:119], v[212:215], v[0:15]
	s_waitcnt vmcnt(12)
	v_mfma_f32_32x32x16_bf16 v[0:15], v[120:123], v[216:219], v[0:15]
	s_waitcnt vmcnt(10)
	v_mfma_f32_32x32x16_bf16 v[0:15], v[124:127], v[220:223], v[0:15]
	s_waitcnt vmcnt(8)
	v_mfma_f32_32x32x16_bf16 v[0:15], v[128:131], v[224:227], v[0:15]
	s_waitcnt vmcnt(6)
	v_mfma_f32_32x32x16_bf16 v[0:15], v[132:135], v[228:231], v[0:15]
	s_waitcnt vmcnt(4)
	v_mfma_f32_32x32x16_bf16 v[0:15], v[136:139], v[232:235], v[0:15]
	s_barrier
	s_waitcnt vmcnt(2)
	v_mfma_f32_32x32x16_bf16 v[0:15], v[140:143], v[236:239], v[0:15]
	s_waitcnt vmcnt(0)
	v_mfma_f32_32x32x16_bf16 v[0:15], v[144:147], v[240:243], v[0:15]
	s_nop 11
	ds_write2st64_b32 v33, v0, v1 offset1:1
	ds_write2st64_b32 v33, v2, v3 offset0:2 offset1:3
	ds_write2st64_b32 v33, v4, v5 offset0:4 offset1:5
	ds_write2st64_b32 v33, v6, v7 offset0:6 offset1:7
	ds_write2st64_b32 v33, v8, v9 offset0:8 offset1:9
	ds_write2st64_b32 v33, v10, v11 offset0:10 offset1:11
	ds_write2st64_b32 v33, v12, v13 offset0:12 offset1:13
	ds_write2st64_b32 v33, v14, v15 offset0:14 offset1:15
	s_waitcnt lgkmcnt(0)
	s_barrier
	ds_read2st64_b32 v[0:1], v22 offset1:16
	ds_read2st64_b32 v[2:3], v22 offset0:32 offset1:48
	ds_read2st64_b32 v[4:5], v22 offset0:64 offset1:80
	s_waitcnt lgkmcnt(2)
	v_add_f32_e32 v0, 0, v0
	v_add_f32_e32 v6, v0, v1
	ds_read2st64_b32 v[0:1], v22 offset0:96 offset1:112
	s_waitcnt lgkmcnt(2)
	v_add_f32_e32 v2, v6, v2
	v_add_f32_e32 v2, v2, v3
	s_waitcnt lgkmcnt(1)
	v_add_f32_e32 v2, v2, v4
	v_add_f32_e32 v2, v2, v5
	s_waitcnt lgkmcnt(0)
	v_add_f32_e32 v0, v2, v0
	v_add_f32_e32 v3, v0, v1
	v_mul_f32_e32 v0, v3, v3
	ds_bpermute_b32 v0, v24, v0
	v_or_b32_e32 v4, s13, v21
	v_bfe_u32 v7, v3, 16, 1
	v_add3_u32 v7, v3, v7, s11
	s_waitcnt lgkmcnt(0)
	v_fmac_f32_e32 v0, v3, v3
	ds_bpermute_b32 v1, v25, v0
	s_waitcnt lgkmcnt(0)
	v_add_f32_e32 v2, v0, v1
	ds_bpermute_b32 v5, v26, v2
	v_subrev_u32_e32 v0, s0, v31
	v_ashrrev_i32_e32 v1, 31, v0
	v_lshl_add_u64 v[0:1], v[0:1], 1, s[2:3]
	s_waitcnt lgkmcnt(0)
	v_add_f32_e32 v5, v2, v5
	ds_bpermute_b32 v6, v27, v5
	v_or_b32_e32 v2, v4, v23
	v_ashrrev_i32_e32 v3, 31, v2
	v_lshlrev_b64 v[8:9], 11, v[2:3]
	v_lshl_add_u64 v[8:9], v[0:1], 0, v[8:9]
	s_waitcnt lgkmcnt(0)
	v_add_f32_e32 v5, v5, v6
	ds_bpermute_b32 v6, v28, v5
	global_store_short_d16_hi v[8:9], v7, off
	s_and_saveexec_b64 s[0:1], vcc
	s_cbranch_execz .LBB0_1298
	v_lshl_add_u64 v[2:3], v[2:3], 2, s[4:5]
	s_waitcnt lgkmcnt(0)
	v_add_f32_e32 v5, v5, v6
	global_atomic_add_f32 v[2:3], v5, off
